# add early layer-1 weight conversion by idle workgroups during the out-GEMM tail (w_out part kept after the barrier)
# baseline (speedup 1.0000x reference)
.LBB0_1680:
	s_lshl_b32 s4, s2, 3
	v_writelane_b32 v255, s4, 46
	v_writelane_b32 v255, s4, 53
	s_lshl_b32 s4, s2, 9
	v_writelane_b32 v255, s4, 47
	v_writelane_b32 v255, s96, 48
	s_mov_b32 s4, 0
	v_writelane_b32 v255, s4, 49
	v_writelane_b32 v255, s4, 52
	s_movk_i32 s4, 0x1310
	v_writelane_b32 v255, s4, 50
	s_movk_i32 s4, 0x130f
	v_writelane_b32 v255, s4, 51
	v_readlane_b32 s4, v255, 26
	s_cmp_lg_u32 s4, -1
	s_cbranch_scc1 .Lw3_ret
	s_cmpk_lg_i32 s96, 0x100
	s_cbranch_scc1 .Lw3_ret
	s_mov_b32 s4, 2
	v_writelane_b32 v255, s4, 52
	s_cmp_lt_i32 s2, 32
	s_cbranch_scc1 .Lw3_ret
	s_sub_i32 s4, s2, 32
	s_lshl_b32 s5, s4, 3
	v_writelane_b32 v255, s5, 46
	v_writelane_b32 v255, s5, 53
	s_lshl_b32 s5, s4, 9
	v_writelane_b32 v255, s5, 47
	s_movk_i32 s5, 0xe0
	v_writelane_b32 v255, s5, 48
	s_movk_i32 s5, 0x1110
	v_writelane_b32 v255, s5, 50
	s_movk_i32 s5, 0x110f
	v_writelane_b32 v255, s5, 51
	s_mov_b32 s5, 1
	v_writelane_b32 v255, s5, 52
	s_movk_i32 s63, 0xff00
	s_movk_i32 s40, 0x2ff
	s_movk_i32 s90, 0x4ff
	s_movk_i32 s91, 0x7ff
	s_movk_i32 s94, 0x9ff
	s_branch .Lw3_conv_entry

.LBB0_1732:
	s_or_b64 exec, exec, s[0:1]
	v_readlane_b32 s98, v255, 52
	s_cmp_eq_u32 s98, 2
	s_cbranch_scc0 .Lw3_s2done
	s_mov_b32 s98, 0x100000
	v_writelane_b32 v255, s98, 46
	s_mov_b32 s98, 0x40000000
	v_writelane_b32 v255, s98, 47
	s_lshl_b32 s98, s2, 3
	v_writelane_b32 v255, s98, 53
	v_writelane_b32 v255, s96, 48
	s_movk_i32 s98, 0x1110
	v_writelane_b32 v255, s98, 49
	s_movk_i32 s98, 0x1310
	v_writelane_b32 v255, s98, 50
	s_movk_i32 s98, 0x130f
	v_writelane_b32 v255, s98, 51
.Lw3_s2done:
	v_readlane_b32 s0, v255, 26
	v_readlane_b32 s1, v255, 27
	s_andn2_b64 vcc, exec, s[0:1]
	s_movk_i32 s25, 0x4000
	v_cndmask_b32_e64 v0, 0, 1, s[0:1]
	v_cmp_ne_u32_e64 s[4:5], 1, v0
	s_waitcnt lgkmcnt(0)
	s_barrier
	s_cbranch_vccnz .LBB0_2233
.Lw3_conv_entry:
	s_mov_b64 s[0:1], s[76:77]
	s_mov_b32 s6, s3
	s_mov_b32 s7, -1
	v_readlane_b32 s25, v255, 48
	v_mbcnt_lo_u32_b32 v0, s7, 0
	v_mbcnt_hi_u32_b32 v0, s7, v0
	v_lshl_add_u32 v3, s6, 6, v0
	s_load_dwordx2 s[6:7], s[0:1], 0xb8
	v_ashrrev_i32_e32 v0, 6, v3
	v_readlane_b32 s8, v255, 46
	s_nop 1
	v_add_u32_e32 v2, s8, v0
	s_movk_i32 s8, 0x810
	v_cmp_gt_i32_e32 vcc, s8, v2
	s_and_saveexec_b64 s[8:9], vcc
	s_cbranch_execz .LBB0_1970
	s_load_dwordx2 s[10:11], s[0:1], 0x40
	s_lshl_b32 s30, s25, 3
	v_lshlrev_b32_e32 v4, 3, v3
	v_lshl_add_u32 v0, v0, 14, 0
	v_and_b32_e32 v5, 31, v3
	s_waitcnt lgkmcnt(0)
	s_add_u32 s10, s10, 0x2a10000
	s_addc_u32 s11, s11, 0
	s_add_u32 s12, s6, 0x12400000
	s_addc_u32 s13, s7, 0
	s_add_u32 s16, s6, 0x10000000
	v_bfe_u32 v20, v3, 5, 1
	v_bfe_u32 v21, v3, 3, 3
	v_and_b32_e32 v4, 56, v4
	s_addc_u32 s17, s7, 0
	v_lshl_add_u32 v6, v5, 2, v0
	v_mul_u32_u24_e32 v7, 0x84, v20
	v_mul_u32_u24_e32 v8, 0x84, v4
	s_add_u32 s18, s6, 0x10500000
	v_lshlrev_b32_e32 v9, 2, v21
	s_addc_u32 s19, s7, 0
	v_add3_u32 v22, v0, v8, v9
	v_or_b32_e32 v23, 8, v21
	v_or_b32_e32 v24, 16, v21
	v_or_b32_e32 v25, 24, v21
	v_bitop3_b32 v26, v21, 15, 24 bitop3:0xc8
	s_mov_b64 s[20:21], 0
	v_add_u32_e32 v27, v6, v7
	s_branch .LBB0_1736

.LBB0_1970:
	s_or_b64 exec, exec, s[8:9]
	v_readlane_b32 s8, v255, 47
	s_nop 1
	v_add_u32_e32 v2, s8, v3
	s_movk_i32 s8, 0x7800
	v_cmp_gt_i32_e32 vcc, s8, v2
	s_and_saveexec_b64 s[8:9], vcc
	s_cbranch_execz .LBB0_1973
	s_lshl_b32 s10, s25, 9
	v_ashrrev_i32_e32 v3, 31, v2
	s_waitcnt lgkmcnt(0)
	v_lshl_add_u64 v[4:5], v[2:3], 4, s[6:7]
	s_mov_b64 s[12:13], 0x12c08000
	s_ashr_i32 s11, s10, 31
	v_lshl_add_u64 v[4:5], v[4:5], 0, s[12:13]
	s_lshl_b64 s[12:13], s[10:11], 4
	s_mov_b64 s[16:17], 0
	v_mov_b32_e32 v0, v2

.LBB0_1981:
	s_or_b64 exec, exec, s[8:9]
	s_mov_b64 s[0:1], s[76:77]
	s_waitcnt lgkmcnt(0)
	s_mov_b32 s6, s3
	s_mov_b32 s7, -1
	v_readlane_b32 s16, v255, 48
	v_mbcnt_lo_u32_b32 v0, s7, 0
	v_mbcnt_hi_u32_b32 v0, s7, v0
	v_lshl_add_u32 v0, s6, 6, v0
	v_readlane_b32 s6, v255, 53
	v_ashrrev_i32_e32 v3, 6, v0
	s_nop 0
	v_add_u32_e32 v2, s6, v3
	v_readlane_b32 s6, v255, 49
	s_nop 1
	v_add_u32_e32 v2, s6, v2
	v_readlane_b32 s6, v255, 50
	s_nop 1
	v_cmp_gt_i32_e32 vcc, s6, v2
	s_and_saveexec_b64 s[6:7], vcc
	s_cbranch_execz .LBB0_2232
	s_load_dwordx2 s[8:9], s[0:1], 0x40
	s_load_dwordx4 s[64:67], s[0:1], 0xa0
	s_lshl_b32 s25, s16, 3
	v_lshl_add_u32 v6, v3, 14, 0
	v_and_b32_e32 v3, 31, v0
	v_bfe_u32 v5, v0, 5, 1
	s_waitcnt lgkmcnt(0)
	s_add_u32 s8, s8, 0x2a10000
	v_lshlrev_b32_e32 v4, 2, v3
	v_mul_u32_u24_e32 v7, 0x84, v5
	v_bfe_u32 v21, v0, 3, 3
	v_lshlrev_b32_e32 v0, 3, v0
	s_addc_u32 s9, s9, 0
	v_add3_u32 v20, v6, v4, v7
	v_and_b32_e32 v4, 56, v0
	s_add_u32 s10, s64, 0x800000
	v_mul_u32_u24_e32 v0, 0x84, v4
	v_lshlrev_b32_e32 v7, 2, v21
	s_addc_u32 s11, s65, 0
	v_add3_u32 v22, v6, v0, v7
	v_mov_b32_e32 v0, 0xfffdde00
	s_add_u32 s12, s66, 0x400000
	v_lshl_add_u32 v27, v2, 5, v0
	v_mov_b32_e32 v0, 0xffffdde0
	s_addc_u32 s13, s67, 0
	v_or_b32_e32 v23, 8, v21
	v_or_b32_e32 v24, 16, v21
	v_or_b32_e32 v25, 24, v21
	v_bitop3_b32 v26, v21, 15, 24 bitop3:0xc8
	s_lshl_b32 s30, s16, 8
	v_lshl_add_u32 v28, v2, 1, v0
	s_lshl_b32 s36, s16, 4
	s_mov_b64 s[16:17], 0
	s_branch .LBB0_1985

.LBB0_1984:
	s_or_b64 exec, exec, s[18:19]
	v_add_u32_e32 v2, s25, v2
	v_readlane_b32 s18, v255, 51
	s_nop 1
	v_cmp_lt_i32_e32 vcc, s18, v2
	v_add_u32_e32 v27, s30, v27
	s_or_b64 s[16:17], vcc, s[16:17]
	v_add_u32_e32 v28, s36, v28
	s_andn2_b64 exec, exec, s[16:17]
	s_cbranch_execz .LBB0_2232

.LBB0_2232:
	s_or_b64 exec, exec, s[6:7]
	v_readlane_b32 s98, v255, 52
	s_cmp_eq_u32 s98, 1
	s_cbranch_scc0 .Lw3_noret
	s_mov_b32 s98, 2
	v_writelane_b32 v255, s98, 52
	s_waitcnt vmcnt(0) lgkmcnt(0)
	s_barrier
	s_branch .Lw3_ret
.Lw3_noret:
	s_movk_i32 s25, 0x4800
	s_waitcnt lgkmcnt(0)
	s_barrier
